# attention GEN steps: bias+mask from a precomputed distance-indexed LDS table (2 VALU + 8 reads), table reads issued ahead of the K reads; 4-slot ring
# speedup vs baseline: 1.0623x; 1.0074x over previous
; #define LAS __attribute__((address_space(3)))
; DI void attn_phase(const Params& p, const int layer, const int wid_s) {
;     ...
;   {
;     const float* tg = (const float*)(p.ws + OFF_TAB);
;     for (int i = tid; i < 8 * 132; i += 512) tab[i] = tg[i];
;   }
;   __syncthreads();
;   if (tid < 8) { float bm = 0.f; for (int i = 0; i <= 128; ++i) bm = fmaxf(bm, tab[tid * 132 + i]); tab[tid * 132 + 129] = bm; tab[tid * 132 + 130] = MASKV; }
;   __syncthreads();
;     ...
;       LAS unsigned char* ring = (LAS unsigned char*)smem + 104576;
;       int k_src_off, v_src_off;
;       { const int r = tid >> 3, cs = tid & 7, c = cs ^ (r & 7); k_src_off = r * LDH + c * 8; }
;       { const int i = tid & 255, r = i >> 2, cs = i & 3, c = cs ^ ((r >> 2) & 3); v_src_off = r * 32 + c * 8; }
;       const unsigned stage_dst = (unsigned)(wave < 4 ? wave * 1024 : 4096 + (wave - 4) * 1024);
;       unsigned kread[2][2], vread[4];
; #pragma unroll
;       for (int kt = 0; kt < 2; ++kt)
; #pragma unroll
;         for (int ks = 0; ks < 2; ++ks) { const int r = kt * 16 + fr, c = ks * 4 + fq; kread[kt][ks] = (unsigned)(r * 128 + ((c ^ (r & 7)) * 16)); }
; #pragma unroll
;       for (int dt = 0; dt < 4; ++dt) { const int r = dt * 16 + fr; vread[dt] = (unsigned)(4096 + r * 64 + ((fq ^ ((r >> 2) & 3)) * 16)); }
.LBB0_189:
	s_or_b64 exec, exec, s[0:1]
	v_mov_b32_e32 v198, v2
	v_min_u32_e32 v198, 0x293, v198
	v_sub_u32_e32 v199, 0x23f, v198
	v_cmp_gt_u32_e32 vcc, s33, v199
	v_min_u32_e32 v200, 0x80, v199
	v_lshlrev_b32_e32 v200, 2, v200
	v_lshlrev_b32_e32 v201, 2, v198
	v_add_u32_e32 v201, 0x22080, v201
	ds_read_b32 v202, v200 offset:0
	ds_read_b32 v203, v200 offset:528
	ds_read_b32 v204, v200 offset:1056
	ds_read_b32 v205, v200 offset:1584
	ds_read_b32 v206, v200 offset:2112
	ds_read_b32 v207, v200 offset:2640
	ds_read_b32 v208, v200 offset:3168
	ds_read_b32 v209, v200 offset:3696
	s_waitcnt lgkmcnt(0)
	v_cndmask_b32_e32 v202, v4, v202, vcc
	v_cndmask_b32_e32 v203, v4, v203, vcc
	v_cndmask_b32_e32 v204, v4, v204, vcc
	v_cndmask_b32_e32 v205, v4, v205, vcc
	v_cndmask_b32_e32 v206, v4, v206, vcc
	v_cndmask_b32_e32 v207, v4, v207, vcc
	v_cndmask_b32_e32 v208, v4, v208, vcc
	v_cndmask_b32_e32 v209, v4, v209, vcc
	ds_write_b32 v201, v202 offset:0
	ds_write_b32 v201, v203 offset:2640
	ds_write_b32 v201, v204 offset:5280
	ds_write_b32 v201, v205 offset:7920
	ds_write_b32 v201, v206 offset:10560
	ds_write_b32 v201, v207 offset:13200
	ds_write_b32 v201, v208 offset:15840
	ds_write_b32 v201, v209 offset:18480
	v_add_u32_e32 v198, 512, v2
	v_min_u32_e32 v198, 0x293, v198
	v_sub_u32_e32 v199, 0x23f, v198
	v_cmp_gt_u32_e32 vcc, s33, v199
	v_min_u32_e32 v200, 0x80, v199
	v_lshlrev_b32_e32 v200, 2, v200
	v_lshlrev_b32_e32 v201, 2, v198
	v_add_u32_e32 v201, 0x22080, v201
	ds_read_b32 v202, v200 offset:0
	ds_read_b32 v203, v200 offset:528
	ds_read_b32 v204, v200 offset:1056
	ds_read_b32 v205, v200 offset:1584
	ds_read_b32 v206, v200 offset:2112
	ds_read_b32 v207, v200 offset:2640
	ds_read_b32 v208, v200 offset:3168
	ds_read_b32 v209, v200 offset:3696
	s_waitcnt lgkmcnt(0)
	v_cndmask_b32_e32 v202, v4, v202, vcc
	v_cndmask_b32_e32 v203, v4, v203, vcc
	v_cndmask_b32_e32 v204, v4, v204, vcc
	v_cndmask_b32_e32 v205, v4, v205, vcc
	v_cndmask_b32_e32 v206, v4, v206, vcc
	v_cndmask_b32_e32 v207, v4, v207, vcc
	v_cndmask_b32_e32 v208, v4, v208, vcc
	v_cndmask_b32_e32 v209, v4, v209, vcc
	ds_write_b32 v201, v202 offset:0
	ds_write_b32 v201, v203 offset:2640
	ds_write_b32 v201, v204 offset:5280
	ds_write_b32 v201, v205 offset:7920
	ds_write_b32 v201, v206 offset:10560
	ds_write_b32 v201, v207 offset:13200
	ds_write_b32 v201, v208 offset:15840
	ds_write_b32 v201, v209 offset:18480
	s_ashr_i32 s0, s6, 6
	s_mul_i32 s1, s0, 0x900
	s_add_i32 s1, s1, 0
	v_and_b32_e32 v3, 63, v2
	v_and_b32_e32 v139, 15, v2
	v_mov_b32_e32 v0, s1
	s_mul_i32 s4, s0, 0x1700
	v_mad_u32_u24 v147, v139, s7, v0
	v_lshlrev_b32_e32 v0, 2, v3
	s_add_i32 s1, s1, s4
	v_readlane_b32 s4, v249, 10
	v_add_u32_e32 v177, 0, v0
	v_add_u32_e32 v178, s1, v0
	v_xor_b32_e32 v179, 64, v0
	v_xor_b32_e32 v180, 0x80, v0
	v_and_b32_e32 v0, 48, v2
	v_readlane_b32 s5, v249, 11
	s_lshl_b32 s1, s0, 4
	s_and_b32 s60, s1, 48
	v_lshl_add_u64 v[142:143], s[4:5], 0, v[0:1]
	v_lshl_add_u32 v0, v2, 2, v157
	s_ashr_i32 s1, s6, 7
	v_and_b32_e32 v181, 0xfc, v0
	v_ashrrev_i32_e32 v0, 3, v2
	s_and_b32 s61, s1, -2
	v_cmp_gt_u32_e64 s[62:63], 16, v3
	v_xor_b32_e32 v3, v0, v2
	s_movk_i32 s1, 0xa00
	v_mul_lo_u32 v0, v0, s1
	v_lshlrev_b32_e32 v3, 3, v3
	s_lshl_b32 s64, s0, 11
	v_and_or_b32 v144, v3, 56, v0
	v_lshrrev_b32_e32 v0, 4, v2
	v_xor_b32_e32 v0, v0, v2
	v_lshlrev_b32_e32 v3, 3, v2
	s_cmp_gt_i32 s0, 3
	v_bfe_u32 v141, v2, 4, 2
	v_and_b32_e32 v3, 0x7e0, v3
	v_lshlrev_b32_e32 v0, 3, v0
	s_cselect_b64 s[30:31], -1, 0
	s_lshl_b32 s22, s0, 10
	s_xor_b32 s0, s64, 0x2000
	v_writelane_b32 v249, s60, 53
	v_and_or_b32 v146, v0, 24, v3
	v_lshlrev_b32_e32 v3, 7, v139
	v_and_b32_e32 v5, 7, v2
	v_lshrrev_b32_e32 v0, 2, v2
	v_add_u32_e32 v182, s0, v177
	v_bitop3_b32 v2, v141, v2, 7 bitop3:0x78
	s_sub_i32 s0, s60, 19
	v_writelane_b32 v249, s61, 54
	v_lshlrev_b32_e32 v140, 6, v139
	v_bitop3_b32 v6, v141, v0, 3 bitop3:0x78
	v_and_b32_e32 v7, 12, v0
	v_lshlrev_b32_e32 v0, 2, v141
	v_bitop3_b32 v5, v141, v5, 4 bitop3:0x36
	v_lshl_or_b32 v185, v2, 4, v3
	v_add_u32_e32 v2, s0, v139
	v_writelane_b32 v249, s62, 55
	v_lshlrev_b32_e32 v138, 3, v141
	v_ashrrev_i32_e32 v145, 31, v144
	v_lshlrev_b32_e32 v148, 5, v139
	v_lshl_or_b32 v183, v6, 4, v140
	s_add_i32 s24, s22, 0x1d880
	v_lshl_or_b32 v184, v5, 4, v3
	v_sub_u32_e32 v186, v2, v7
	s_mov_b32 s0, 0
	v_lshlrev_b32_e32 v150, 1, v0
	s_mov_b32 s23, 0
	v_writelane_b32 v249, s63, 56
	s_waitcnt lgkmcnt(0)
	s_barrier
	v_writelane_b32 v249, s64, 57
	s_branch .LBB0_192

; #define RING_ISSUE(SI) do { int kbi = kb0 + (SI) * 32; if (kbi > kb_last) kbi = kb_last; const int slot = (SI) % 3; \
;           const h16* srcp = wave < 4 ? kbase + (size_t)kbi * LDH + k_src_off : vT + (size_t)(kbi >> 5) * 2048 + v_src_off; \
;           __builtin_amdgcn_global_load_lds((const unsigned*)srcp, (LAS unsigned*)(ring + slot * 8192 + stage_dst), 16, 0, 0); } while (0)
; DI void attn_phase(const Params& p, const int layer, const int wid_s) {
;     ...
;         int kb0 = 0, lo_w = 0;
;         if (br == 2) { kb0 = qblk * 64 - 512; if (kb0 < 0) kb0 = 0; lo_w = t0 - 511; if (lo_w < 0) lo_w = 0; lo_w &= ~31; }
;         const int nsteps = (kb_last - kb0) / 32 + 1;
;         f32x4 O[2][4]; float l[2];
; #pragma unroll
;         for (int hp = 0; hp < 2; ++hp) { l[hp] = 0.f;
; #pragma unroll
;           for (int dt = 0; dt < 4; ++dt) O[hp][dt] = (f32x4){0.f, 0.f, 0.f, 0.f}; }
;     ...
;         asm volatile("s_waitcnt vmcnt(0)" ::: "memory");
;         __syncthreads();
;         RING_ISSUE(0); RING_ISSUE(1);
.LBB0_345:
	s_add_i32 m0, s13, 0x1b880
	s_sub_i32 s13, s14, s12
	global_load_lds_dwordx4 v[2:3], off
	s_xor_b64 s[6:7], s[4:5], -1
	s_ashr_i32 s13, s13, 5
	v_mov_b32_e32 v3, 0
	s_cmp_lt_i32 s13, 0
	v_mov_b32_e32 v2, v3
	v_mov_b32_e32 v67, v3
	v_mov_b32_e32 v66, v3
	v_mov_b32_e32 v65, v3
	v_mov_b32_e32 v64, v3
	v_mov_b32_e32 v59, v3
	v_mov_b32_e32 v58, v3
	v_mov_b32_e32 v57, v3
	v_mov_b32_e32 v56, v3
	v_mov_b32_e32 v55, v3
	v_mov_b32_e32 v54, v3
	v_mov_b32_e32 v53, v3
	v_mov_b32_e32 v52, v3
	v_mov_b32_e32 v51, v3
	v_mov_b32_e32 v50, v3
	v_mov_b32_e32 v49, v3
	v_mov_b32_e32 v48, v3
	v_mov_b32_e32 v47, v3
	v_mov_b32_e32 v46, v3
	v_mov_b32_e32 v45, v3
	v_mov_b32_e32 v44, v3
	v_mov_b32_e32 v43, v3
	v_mov_b32_e32 v42, v3
	v_mov_b32_e32 v41, v3
	v_mov_b32_e32 v40, v3
	v_mov_b32_e32 v39, v3
	v_mov_b32_e32 v38, v3
	v_mov_b32_e32 v37, v3
	v_mov_b32_e32 v36, v3
	v_mov_b32_e32 v35, v3
	v_mov_b32_e32 v34, v3
	v_mov_b32_e32 v33, v3
	v_mov_b32_e32 v32, v3
	s_cbranch_scc1 .LBB0_368
	v_mov_b32_e32 v2, v1
	v_mov_b32_e32 v3, v1
	s_and_b64 s[40:41], s[4:5], exec
	v_lshl_add_u64 v[6:7], s[10:11], 0, v[0:1]
	v_mov_b32_e32 v0, v1
	v_mov_b32_e32 v32, 0
	v_mov_b64_e32 v[62:63], v[2:3]
	s_mov_b32 s39, 0
	s_cselect_b32 s40, s21, 0
	v_lshl_add_u64 v[152:153], v[144:145], 1, s[8:9]
	s_add_i32 s41, s13, 1
	s_add_i32 s42, s12, 0x1f1
	v_subrev_u32_e32 v151, s12, v195
	s_mov_b32 s43, 2
	s_mov_b32 s44, 0
	v_mov_b64_e32 v[60:61], v[0:1]
	v_mov_b32_e32 v33, v32
	v_mov_b32_e32 v34, v32
	v_mov_b32_e32 v35, v32
	v_mov_b32_e32 v48, v32
	v_mov_b32_e32 v49, v32
	v_mov_b32_e32 v50, v32
	v_mov_b32_e32 v51, v32
	v_mov_b32_e32 v36, v32
	v_mov_b32_e32 v37, v32
	v_mov_b32_e32 v38, v32
	v_mov_b32_e32 v39, v32
	v_mov_b32_e32 v52, v32
	v_mov_b32_e32 v53, v32
	v_mov_b32_e32 v54, v32
	v_mov_b32_e32 v55, v32
	v_mov_b32_e32 v40, v32
	v_mov_b32_e32 v41, v32
	v_mov_b32_e32 v42, v32
	v_mov_b32_e32 v43, v32
	v_mov_b32_e32 v56, v32
	v_mov_b32_e32 v57, v32
	v_mov_b32_e32 v58, v32
	v_mov_b32_e32 v59, v32
	v_mov_b32_e32 v44, v32
	v_mov_b32_e32 v45, v32
	v_mov_b32_e32 v46, v32
	v_mov_b32_e32 v47, v32
	v_mov_b32_e32 v2, v32
	v_mov_b32_e32 v3, v32
	v_mov_b32_e32 v64, v32
	v_mov_b32_e32 v65, v32
	v_mov_b32_e32 v66, v32
	v_mov_b32_e32 v67, v32
	s_movk_i32 s42, 0x1400
	s_and_b64 vcc, exec, s[30:31]
	s_cselect_b32 s42, 0x80, s42
	v_cndmask_b32_e32 v240, v152, v6, vcc
	v_cndmask_b32_e32 v241, v153, v7, vcc
	s_mov_b32 s45, s12
	s_mov_b32 s39, 0x19880
	s_mov_b32 s43, 0x1d880
	s_mov_b32 s44, 0
	s_mov_b32 s13, -1
	v_mov_b32_e32 v214, 0
	v_mov_b32_e32 v215, 0
	v_mov_b32_e32 v216, 0
	v_mov_b32_e32 v217, 0
	v_mov_b32_e32 v218, 0
	v_mov_b32_e32 v219, 0
	v_mov_b32_e32 v220, 0
	v_mov_b32_e32 v221, 0
	v_lshlrev_b32_e32 v246, 2, v195
	v_sub_u32_e32 v246, 0, v246
	s_and_b64 vcc, exec, s[4:5]
	s_cbranch_vccnz .Lat_prewin
	v_mov_b32_e32 v242, v193
	v_mov_b32_e32 v243, v194
	v_mov_b32_e32 v244, v5
	v_bfrev_b32_e32 v247, 1
	s_branch .Lat_precls

; template <bool SEL, bool GEN>
; DI void attn_step(const KF& kv, const int kb, const int t, const int lane, const bool selbit,
;                   const LAS float* tabh, const half8 (&q)[2][2], f32x4 (&O)[2][4], const float (&nR)[2], float (&l)[2]) {
;     ...
;   if (GEN) {
;     const int d0 = t - kb - fq * 4;
; #pragma unroll
;     for (int kt = 0; kt < 2; ++kt)
; #pragma unroll
;       for (int j = 0; j < 4; ++j) {
;         const int dist = d0 - (kt * 16 + j);
;         const bool bad = SEL ? (dist < 0) : ((unsigned)dist >= 512u);
;         const int ix = bad ? 130 : (dist > 128 ? 128 : dist);
; #pragma unroll
;         for (int hp = 0; hp < 2; ++hp) s[hp][kt][j] += tabh[hp * 132 + ix];
;       }
;   }
;   half8 pf[2];
; #pragma unroll
;   for (int hp = 0; hp < 2; ++hp) {
;     f32x4 p0, p1;
; #pragma unroll
;     for (int j = 0; j < 4; ++j) { p0[j] = __builtin_amdgcn_exp2f(s[hp][0][j]); p1[j] = __builtin_amdgcn_exp2f(s[hp][1][j]); }
; DI void attn_phase(const Params& p, const int layer, const int wid_s) {
;     ...
;         for (int si = 0; si < nsteps; ++si) {
;           asm volatile("s_waitcnt vmcnt(1) lgkmcnt(0)" ::: "memory");
;           __builtin_amdgcn_s_barrier();
;           asm volatile("" ::: "memory");
;           RING_ISSUE(si + 2);
;           const int kb = kb0 + si * 32;
;           if (kb > kmax_w || kb < lo_w) continue;
;           if (br == 1 && kb + 31 + 128 <= t0 && __ballot((selmask >> (kb >> 6)) & 1u) == 0ull) continue;
;           LAS unsigned char* slotp = ring + (si % 3) * 8192;
;           KF kv;
; #pragma unroll
;           for (int kt = 0; kt < 2; ++kt)
; #pragma unroll
;             for (int ks = 0; ks < 2; ++ks) kv.k[kt][ks] = *(const LAS half8*)(slotp + kread[kt][ks]);
; #pragma unroll
;           for (int dt = 0; dt < 4; ++dt) kv.v[dt] = *(const LAS half8*)(slotp + vread[dt]);
;           if (br == 1) {
;             const bool bit = (selmask >> (kb >> 6)) & 1u;
;             if (kb + 31 + 128 <= t0) attn_step<true, false>(kv, kb, t, lane, bit, tabh, q, O, nRs, l);
;             else attn_step<true, true>(kv, kb, t, lane, bit, tabh, q, O, nRs, l);
;           } else {
;             const bool gen = (kb + 31 + 128 > t0) || (kb + 512 <= t0 + 15);
;             if (!gen) attn_step<false, false>(kv, kb, t, lane, true, tabh, q, O, nRw, l);
;             else attn_step<false, true>(kv, kb, t, lane, true, tabh, q, O, nRw, l);
;           }
.Lat_xtop:
	s_waitcnt vmcnt(1)
	s_barrier
	s_bitcmp1_b32 s44, 1
	s_cbranch_scc0 .Lat_nogi_xt
	s_mul_i32 s8, s38, 5
	s_lshl_b32 s9, s45, 2
	s_add_i32 s8, s8, s9
	s_add_i32 s8, s8, 0x228b0
	v_add_u32_e32 v116, s8, v246
	v_add_u32_e32 v117, 0xa50, v116
	ds_read2_b32 v[222:223], v116 offset0:0 offset1:1
	ds_read2_b32 v[224:225], v116 offset0:2 offset1:3
	ds_read2_b32 v[226:227], v116 offset0:16 offset1:17
	ds_read2_b32 v[228:229], v116 offset0:18 offset1:19
	ds_read2_b32 v[230:231], v117 offset0:0 offset1:1
	ds_read2_b32 v[232:233], v117 offset0:2 offset1:3
	ds_read2_b32 v[234:235], v117 offset0:16 offset1:17
	ds_read2_b32 v[236:237], v117 offset0:18 offset1:19
.Lat_nogi_xt:
	s_bitcmp1_b32 s12, 0
	s_cbranch_scc0 .Lat_xskip
	v_add_u32_e32 v0, s39, v185
	v_add_u32_e32 v64, s39, v184
	v_add_u32_e32 v65, s39, v183
	ds_read_b128 v[96:99], v0
	ds_read_b128 v[92:95], v64
	ds_read_b128 v[88:91], v0 offset:2048
	ds_read_b128 v[84:87], v64 offset:2048
	s_lshr_b32 s10, s45, 6
	s_cmp_eq_u32 s10, s13
	s_cbranch_scc1 .Lat_cok_x
	s_mov_b32 s13, s10
	v_bfe_u32 v66, v244, s10, 1
	v_cmp_ne_u32_e32 vcc, 0, v66
	s_nop 1
	v_cndmask_b32_e32 v128, v4, v242, vcc
	v_cndmask_b32_e32 v132, v4, v243, vcc
	v_cndmask_b32_e32 v129, v4, v242, vcc
	v_cndmask_b32_e32 v133, v4, v243, vcc
	v_cndmask_b32_e32 v130, v4, v242, vcc
	v_cndmask_b32_e32 v134, v4, v243, vcc
	v_cndmask_b32_e32 v131, v4, v242, vcc
	v_cndmask_b32_e32 v135, v4, v243, vcc
.Lat_cok_x:
	s_bitcmp1_b32 s44, 0
	s_cbranch_scc0 .Lat_xb
	s_bitcmp1_b32 s44, 1
	s_cbranch_scc0 .Lat_noga_xa
	s_waitcnt lgkmcnt(4)
	v_add_f32_e32 v100, v100, v222
	v_add_f32_e32 v101, v101, v223
	v_add_f32_e32 v102, v102, v224
	v_add_f32_e32 v103, v103, v225
	v_add_f32_e32 v104, v104, v226
	v_add_f32_e32 v105, v105, v227
	v_add_f32_e32 v106, v106, v228
	v_add_f32_e32 v107, v107, v229
	v_add_f32_e32 v108, v108, v230
	v_add_f32_e32 v109, v109, v231
	v_add_f32_e32 v110, v110, v232
	v_add_f32_e32 v111, v111, v233
	v_add_f32_e32 v112, v112, v234
	v_add_f32_e32 v113, v113, v235
	v_add_f32_e32 v114, v114, v236
	v_add_f32_e32 v115, v115, v237
.Lat_noga_xa:
	v_exp_f32_e32 v198, v100
	v_exp_f32_e32 v199, v101
	v_exp_f32_e32 v200, v102
	v_exp_f32_e32 v201, v103
	v_exp_f32_e32 v202, v104
	v_exp_f32_e32 v203, v105
	v_exp_f32_e32 v204, v106
	v_exp_f32_e32 v205, v107
	v_exp_f32_e32 v206, v108
	v_exp_f32_e32 v207, v109
	v_exp_f32_e32 v208, v110
	v_exp_f32_e32 v209, v111
	v_exp_f32_e32 v210, v112
	v_exp_f32_e32 v211, v113
	v_exp_f32_e32 v212, v114
	v_exp_f32_e32 v213, v115
	v_cvt_pkrtz_f16_f32 v120, v198, v199
	v_cvt_pkrtz_f16_f32 v121, v200, v201
	v_cvt_pkrtz_f16_f32 v122, v202, v203
	v_cvt_pkrtz_f16_f32 v123, v204, v205
	v_cvt_pkrtz_f16_f32 v124, v206, v207
	v_cvt_pkrtz_f16_f32 v125, v208, v209
	v_cvt_pkrtz_f16_f32 v126, v210, v211
	v_cvt_pkrtz_f16_f32 v127, v212, v213
	s_waitcnt lgkmcnt(0)
	v_mfma_f32_16x16x32_f16 v[60:63], v[80:83], v[120:123], v[60:63]
	v_add_f32_e32 v214, v214, v198
	v_add_f32_e32 v215, v215, v199
	v_add_f32_e32 v216, v216, v200
	v_mfma_f32_16x16x32_f16 v[56:59], v[76:79], v[120:123], v[56:59]
	v_add_f32_e32 v217, v217, v201
	v_add_f32_e32 v214, v214, v202
	v_add_f32_e32 v215, v215, v203
	v_mfma_f32_16x16x32_f16 v[52:55], v[72:75], v[120:123], v[52:55]
	v_add_f32_e32 v216, v216, v204
	v_add_f32_e32 v217, v217, v205
	v_add_f32_e32 v218, v218, v206
	v_mfma_f32_16x16x32_f16 v[48:51], v[68:71], v[120:123], v[48:51]
	v_add_f32_e32 v219, v219, v207
	v_add_f32_e32 v220, v220, v208
	v_add_f32_e32 v221, v221, v209
	v_mfma_f32_16x16x32_f16 v[44:47], v[80:83], v[124:127], v[44:47]
	v_add_f32_e32 v218, v218, v210
	v_add_f32_e32 v219, v219, v211
	v_add_f32_e32 v220, v220, v212
	v_mfma_f32_16x16x32_f16 v[40:43], v[76:79], v[124:127], v[40:43]
	v_add_f32_e32 v221, v221, v213
	s_add_i32 s8, s45, 64
	s_min_i32 s8, s8, s14
	v_mfma_f32_16x16x32_f16 v[36:39], v[72:75], v[124:127], v[36:39]
	s_mul_i32 s8, s8, s42
	s_mov_b32 s9, 0
	v_lshl_add_u64 v[238:239], v[240:241], 0, s[8:9]
	v_mfma_f32_16x16x32_f16 v[32:35], v[68:71], v[124:127], v[32:35]
	s_add_i32 m0, s43, s22
	s_nop 0
	global_load_lds_dwordx4 v[238:239], off
	s_and_b32 s44, s12, 2
	s_or_b32 s44, s44, 1
	v_mfma_f32_16x16x32_f16 v[100:103], v[96:99], v[8:11], v[128:131]
	s_add_i32 s43, s43, 0x2000
	s_cmp_eq_u32 s43, 0x1f880
	s_cselect_b32 s43, 0x20080, s43
	s_cmp_eq_u32 s43, 0x22080
	v_mfma_f32_16x16x32_f16 v[104:107], v[88:91], v[8:11], v[128:131]
	s_cselect_b32 s43, 0x19880, s43
	s_add_i32 s39, s39, 0x2000
	s_cmp_eq_u32 s39, 0x1f880
	s_cselect_b32 s39, 0x20080, s39
	v_mfma_f32_16x16x32_f16 v[108:111], v[96:99], v[16:19], v[132:135]
	s_cmp_eq_u32 s39, 0x22080
	s_cselect_b32 s39, 0x19880, s39
	s_add_i32 s45, s45, 32
	s_add_i32 s41, s41, -1
	v_mfma_f32_16x16x32_f16 v[112:115], v[88:91], v[16:19], v[132:135]
	s_add_i32 s10, s45, 0x9f
	s_cmp_gt_i32 s10, s51
	s_cselect_b32 s11, 2, 0
	s_add_i32 s10, s45, 0x1f1
	v_mfma_f32_16x16x32_f16 v[100:103], v[92:95], v[12:15], v[100:103]
	s_cmp_le_i32 s10, s51
	s_cselect_b32 s10, 2, 0
	s_and_b32 s10, s10, s4
	s_or_b32 s11, s11, s10
	v_mfma_f32_16x16x32_f16 v[104:107], v[84:87], v[12:15], v[104:107]
	s_lshr_b32 s10, s45, 6
	v_bfe_u32 v0, v244, s10, 1
	v_cmp_ne_u32_e32 vcc, 0, v0
	s_cmp_lg_u64 vcc, 0
	v_mfma_f32_16x16x32_f16 v[108:111], v[92:95], v[20:23], v[108:111]
	s_cselect_b32 s10, 1, 0
	s_lshr_b32 s9, s11, 1
	s_or_b32 s10, s10, s9
	s_cmp_le_i32 s45, s15
	v_mfma_f32_16x16x32_f16 v[112:115], v[84:87], v[20:23], v[112:115]
	s_cselect_b32 s10, s10, 0
	s_cmp_ge_i32 s45, s40
	s_cselect_b32 s10, s10, 0
	s_or_b32 s12, s11, s10
	ds_read_b128 v[80:83], v65 offset:4096
	ds_read_b128 v[76:79], v65 offset:5120
	ds_read_b128 v[72:75], v65 offset:6144
	ds_read_b128 v[68:71], v65 offset:7168
	s_cmp_lg_u32 s41, 0
	s_cbranch_scc1 .Lat_xtop
	s_branch .Lat_xexit
; template <bool SEL, bool GEN>
; DI void attn_step(const KF& kv, const int kb, const int t, const int lane, const bool selbit,
;                   const LAS float* tabh, const half8 (&q)[2][2], f32x4 (&O)[2][4], const float (&nR)[2], float (&l)[2]) {
;     ...
;   for (int hp = 0; hp < 2; ++hp) {
;     float nm = nR[hp];
;     if (SEL) nm = selbit ? nm : MASKV;
;     const f32x4 c0 = {nm, nm, nm, nm};
; #pragma unroll
;     for (int kt = 0; kt < 2; ++kt) {
;       s[hp][kt] = MFMA16(kv.k[kt][0], q[hp][0], c0);
;       s[hp][kt] = MFMA16(kv.k[kt][1], q[hp][1], s[hp][kt]);
;     }
;   }
;   if (GEN) {
;     const int d0 = t - kb - fq * 4;
; #pragma unroll
;     for (int kt = 0; kt < 2; ++kt)
; #pragma unroll
;       for (int j = 0; j < 4; ++j) {
;         const int dist = d0 - (kt * 16 + j);
; DI void attn_phase(const Params& p, const int layer, const int wid_s) {
;     ...
;         asm volatile("s_waitcnt vmcnt(0)" ::: "memory");
;         __syncthreads();
;         RING_ISSUE(0); RING_ISSUE(1);
; #pragma unroll 1
;         for (int si = 0; si < nsteps; ++si) {
;           asm volatile("s_waitcnt vmcnt(1) lgkmcnt(0)" ::: "memory");
;           __builtin_amdgcn_s_barrier();
;           asm volatile("" ::: "memory");
;           RING_ISSUE(si + 2);
;           const int kb = kb0 + si * 32;
;           if (kb > kmax_w || kb < lo_w) continue;
;           if (br == 1 && kb + 31 + 128 <= t0 && __ballot((selmask >> (kb >> 6)) & 1u) == 0ull) continue;
;           LAS unsigned char* slotp = ring + (si % 3) * 8192;
;           KF kv;
; #pragma unroll
;           for (int kt = 0; kt < 2; ++kt)
; #pragma unroll
;             for (int ks = 0; ks < 2; ++ks) kv.k[kt][ks] = *(const LAS half8*)(slotp + kread[kt][ks]);
; #pragma unroll
;           for (int dt = 0; dt < 4; ++dt) kv.v[dt] = *(const LAS half8*)(slotp + vread[dt]);
;           if (br == 1) {
;             const bool bit = (selmask >> (kb >> 6)) & 1u;
;             if (kb + 31 + 128 <= t0) attn_step<true, false>(kv, kb, t, lane, bit, tabh, q, O, nRs, l);
;             else attn_step<true, true>(kv, kb, t, lane, bit, tabh, q, O, nRs, l);
;           } else {
;             const bool gen = (kb + 31 + 128 > t0) || (kb + 512 <= t0 + 15);
;             if (!gen) attn_step<false, false>(kv, kb, t, lane, true, tabh, q, O, nRw, l);
;             else attn_step<false, true>(kv, kb, t, lane, true, tabh, q, O, nRw, l);
;           }
.Lat_xb:
	s_waitcnt lgkmcnt(0)
	s_and_b32 s44, s12, 2
	s_or_b32 s44, s44, 1
	v_mfma_f32_16x16x32_f16 v[100:103], v[96:99], v[8:11], v[128:131]
	s_add_i32 s8, s45, 64
	s_min_i32 s8, s8, s14
	s_mul_i32 s8, s8, s42
	s_mov_b32 s9, 0
	v_lshl_add_u64 v[238:239], v[240:241], 0, s[8:9]
	v_mfma_f32_16x16x32_f16 v[104:107], v[88:91], v[8:11], v[128:131]
	s_add_i32 m0, s43, s22
	s_nop 0
	global_load_lds_dwordx4 v[238:239], off
	s_add_i32 s43, s43, 0x2000
	s_cmp_eq_u32 s43, 0x1f880
	v_mfma_f32_16x16x32_f16 v[108:111], v[96:99], v[16:19], v[132:135]
	s_cselect_b32 s43, 0x20080, s43
	s_cmp_eq_u32 s43, 0x22080
	s_cselect_b32 s43, 0x19880, s43
	s_add_i32 s39, s39, 0x2000
	s_cmp_eq_u32 s39, 0x1f880
	v_mfma_f32_16x16x32_f16 v[112:115], v[88:91], v[16:19], v[132:135]
	s_cselect_b32 s39, 0x20080, s39
	s_cmp_eq_u32 s39, 0x22080
	s_cselect_b32 s39, 0x19880, s39
	s_add_i32 s45, s45, 32
	s_add_i32 s41, s41, -1
	v_mfma_f32_16x16x32_f16 v[100:103], v[92:95], v[12:15], v[100:103]
	s_add_i32 s10, s45, 0x9f
	s_cmp_gt_i32 s10, s51
	s_cselect_b32 s11, 2, 0
	s_add_i32 s10, s45, 0x1f1
	s_cmp_le_i32 s10, s51
	v_mfma_f32_16x16x32_f16 v[104:107], v[84:87], v[12:15], v[104:107]
	s_cselect_b32 s10, 2, 0
	s_and_b32 s10, s10, s4
	s_or_b32 s11, s11, s10
	s_lshr_b32 s10, s45, 6
	v_bfe_u32 v0, v244, s10, 1
	v_mfma_f32_16x16x32_f16 v[108:111], v[92:95], v[20:23], v[108:111]
	v_cmp_ne_u32_e32 vcc, 0, v0
	s_cmp_lg_u64 vcc, 0
	s_cselect_b32 s10, 1, 0
	s_lshr_b32 s9, s11, 1
	s_or_b32 s10, s10, s9
	v_mfma_f32_16x16x32_f16 v[112:115], v[84:87], v[20:23], v[112:115]
	s_cmp_le_i32 s45, s15
	s_cselect_b32 s10, s10, 0
	s_cmp_ge_i32 s45, s40
	s_cselect_b32 s10, s10, 0
	s_or_b32 s12, s11, s10
	ds_read_b128 v[80:83], v65 offset:4096
	ds_read_b128 v[76:79], v65 offset:5120
	ds_read_b128 v[72:75], v65 offset:6144
	ds_read_b128 v[68:71], v65 offset:7168
	s_cmp_lg_u32 s41, 0
	s_cbranch_scc1 .Lat_xtop
	s_branch .Lat_xexit
.Lat_xskip:
	s_bitcmp1_b32 s44, 0
	s_cbranch_scc0 .Lat_xd
	s_bitcmp1_b32 s44, 1
	s_cbranch_scc0 .Lat_noga_xc
	s_waitcnt lgkmcnt(0)
	v_add_f32_e32 v100, v100, v222
	v_add_f32_e32 v101, v101, v223
	v_add_f32_e32 v102, v102, v224
	v_add_f32_e32 v103, v103, v225
	v_add_f32_e32 v104, v104, v226
	v_add_f32_e32 v105, v105, v227
	v_add_f32_e32 v106, v106, v228
	v_add_f32_e32 v107, v107, v229
	v_add_f32_e32 v108, v108, v230
	v_add_f32_e32 v109, v109, v231
	v_add_f32_e32 v110, v110, v232
	v_add_f32_e32 v111, v111, v233
	v_add_f32_e32 v112, v112, v234
	v_add_f32_e32 v113, v113, v235
	v_add_f32_e32 v114, v114, v236
	v_add_f32_e32 v115, v115, v237
; #define LAS __attribute__((address_space(3)))
; template <bool SEL, bool GEN>
; DI void attn_step(const KF& kv, const int kb, const int t, const int lane, const bool selbit,
;                   const LAS float* tabh, const half8 (&q)[2][2], f32x4 (&O)[2][4], const float (&nR)[2], float (&l)[2]) {
;     ...
;   for (int hp = 0; hp < 2; ++hp) {
;     f32x4 p0, p1;
; #pragma unroll
;     for (int j = 0; j < 4; ++j) { p0[j] = __builtin_amdgcn_exp2f(s[hp][0][j]); p1[j] = __builtin_amdgcn_exp2f(s[hp][1][j]); }
;     l[hp] += ((p0[0] + p0[1]) + (p0[2] + p0[3])) + ((p1[0] + p1[1]) + (p1[2] + p1[3]));
;     pf[hp] = pack8(p0, p1);
;   }
; #pragma unroll
;   for (int dt = 0; dt < 4; ++dt)
; #pragma unroll
;     for (int hp = 0; hp < 2; ++hp) O[hp][dt] = MFMA16(kv.v[dt], pf[hp], O[hp][dt]);
; DI void attn_phase(const Params& p, const int layer, const int wid_s) {
;     ...
;         asm volatile("s_waitcnt vmcnt(0)" ::: "memory");
;         __syncthreads();
;         RING_ISSUE(0); RING_ISSUE(1);
; #pragma unroll 1
;         for (int si = 0; si < nsteps; ++si) {
;           asm volatile("s_waitcnt vmcnt(1) lgkmcnt(0)" ::: "memory");
;           __builtin_amdgcn_s_barrier();
;           asm volatile("" ::: "memory");
;           RING_ISSUE(si + 2);
;           const int kb = kb0 + si * 32;
;           if (kb > kmax_w || kb < lo_w) continue;
;           if (br == 1 && kb + 31 + 128 <= t0 && __ballot((selmask >> (kb >> 6)) & 1u) == 0ull) continue;
;           LAS unsigned char* slotp = ring + (si % 3) * 8192;
;           KF kv;
; #pragma unroll
;           for (int kt = 0; kt < 2; ++kt)
; #pragma unroll
;             for (int ks = 0; ks < 2; ++ks) kv.k[kt][ks] = *(const LAS half8*)(slotp + kread[kt][ks]);
; #pragma unroll
;           for (int dt = 0; dt < 4; ++dt) kv.v[dt] = *(const LAS half8*)(slotp + vread[dt]);
;           if (br == 1) {
;             const bool bit = (selmask >> (kb >> 6)) & 1u;
;             if (kb + 31 + 128 <= t0) attn_step<true, false>(kv, kb, t, lane, bit, tabh, q, O, nRs, l);
;             else attn_step<true, true>(kv, kb, t, lane, bit, tabh, q, O, nRs, l);
;           } else {
;             const bool gen = (kb + 31 + 128 > t0) || (kb + 512 <= t0 + 15);
;             if (!gen) attn_step<false, false>(kv, kb, t, lane, true, tabh, q, O, nRw, l);
;             else attn_step<false, true>(kv, kb, t, lane, true, tabh, q, O, nRw, l);
;           }
.Lat_noga_xc:
	v_exp_f32_e32 v198, v100
	v_exp_f32_e32 v199, v101
	v_exp_f32_e32 v200, v102
	v_exp_f32_e32 v201, v103
	v_exp_f32_e32 v202, v104
	v_exp_f32_e32 v203, v105
	v_exp_f32_e32 v204, v106
	v_exp_f32_e32 v205, v107
	v_exp_f32_e32 v206, v108
	v_exp_f32_e32 v207, v109
	v_exp_f32_e32 v208, v110
	v_exp_f32_e32 v209, v111
	v_exp_f32_e32 v210, v112
	v_exp_f32_e32 v211, v113
	v_exp_f32_e32 v212, v114
	v_exp_f32_e32 v213, v115
	v_cvt_pkrtz_f16_f32 v120, v198, v199
	v_cvt_pkrtz_f16_f32 v121, v200, v201
	v_cvt_pkrtz_f16_f32 v122, v202, v203
	v_cvt_pkrtz_f16_f32 v123, v204, v205
	v_cvt_pkrtz_f16_f32 v124, v206, v207
	v_cvt_pkrtz_f16_f32 v125, v208, v209
	v_cvt_pkrtz_f16_f32 v126, v210, v211
	v_cvt_pkrtz_f16_f32 v127, v212, v213
	s_waitcnt lgkmcnt(0)
	v_mfma_f32_16x16x32_f16 v[60:63], v[80:83], v[120:123], v[60:63]
	v_add_f32_e32 v214, v214, v198
	v_add_f32_e32 v215, v215, v199
	v_add_f32_e32 v216, v216, v200
	v_add_f32_e32 v217, v217, v201
	v_add_f32_e32 v214, v214, v202
	v_add_f32_e32 v215, v215, v203
	v_add_f32_e32 v216, v216, v204
	v_mfma_f32_16x16x32_f16 v[56:59], v[76:79], v[120:123], v[56:59]
	v_add_f32_e32 v217, v217, v205
	v_add_f32_e32 v218, v218, v206
	v_add_f32_e32 v219, v219, v207
	v_add_f32_e32 v220, v220, v208
	v_add_f32_e32 v221, v221, v209
	v_add_f32_e32 v218, v218, v210
	v_add_f32_e32 v219, v219, v211
	v_mfma_f32_16x16x32_f16 v[52:55], v[72:75], v[120:123], v[52:55]
	v_add_f32_e32 v220, v220, v212
	v_add_f32_e32 v221, v221, v213
	s_add_i32 s8, s45, 64
	s_min_i32 s8, s8, s14
	s_mul_i32 s8, s8, s42
	s_mov_b32 s9, 0
	v_lshl_add_u64 v[238:239], v[240:241], 0, s[8:9]
	v_mfma_f32_16x16x32_f16 v[48:51], v[68:71], v[120:123], v[48:51]
	s_add_i32 m0, s43, s22
	s_nop 0
	global_load_lds_dwordx4 v[238:239], off
	s_add_i32 s43, s43, 0x2000
	s_cmp_eq_u32 s43, 0x1f880
	s_cselect_b32 s43, 0x20080, s43
	s_cmp_eq_u32 s43, 0x22080
	v_mfma_f32_16x16x32_f16 v[44:47], v[80:83], v[124:127], v[44:47]
	s_cselect_b32 s43, 0x19880, s43
	s_add_i32 s39, s39, 0x2000
	s_cmp_eq_u32 s39, 0x1f880
	s_cselect_b32 s39, 0x20080, s39
	s_cmp_eq_u32 s39, 0x22080
	s_cselect_b32 s39, 0x19880, s39
	s_add_i32 s45, s45, 32
	v_mfma_f32_16x16x32_f16 v[40:43], v[76:79], v[124:127], v[40:43]
	s_add_i32 s41, s41, -1
	s_add_i32 s10, s45, 0x9f
	s_cmp_gt_i32 s10, s51
	s_cselect_b32 s11, 2, 0
	s_add_i32 s10, s45, 0x1f1
	s_cmp_le_i32 s10, s51
	s_cselect_b32 s10, 2, 0
	v_mfma_f32_16x16x32_f16 v[36:39], v[72:75], v[124:127], v[36:39]
	s_and_b32 s10, s10, s4
	s_or_b32 s11, s11, s10
	s_lshr_b32 s10, s45, 6
	v_bfe_u32 v0, v244, s10, 1
	v_cmp_ne_u32_e32 vcc, 0, v0
	s_cmp_lg_u64 vcc, 0
	s_cselect_b32 s10, 1, 0
	v_mfma_f32_16x16x32_f16 v[32:35], v[68:71], v[124:127], v[32:35]
	s_lshr_b32 s9, s11, 1
	s_or_b32 s10, s10, s9
	s_cmp_le_i32 s45, s15
	s_cselect_b32 s10, s10, 0
	s_cmp_ge_i32 s45, s40
	s_cselect_b32 s10, s10, 0
	s_or_b32 s12, s11, s10
	s_mov_b32 s44, 0
	s_cmp_lg_u32 s41, 0
	s_cbranch_scc1 .Lat_xtop
	s_branch .Lat_xexit
.Lat_xd:
	s_add_i32 s8, s45, 64
	s_min_i32 s8, s8, s14
	s_mul_i32 s8, s8, s42
	s_mov_b32 s9, 0
	v_lshl_add_u64 v[238:239], v[240:241], 0, s[8:9]
	s_add_i32 m0, s43, s22
	s_nop 0
	global_load_lds_dwordx4 v[238:239], off
	s_add_i32 s43, s43, 0x2000
	s_cmp_eq_u32 s43, 0x1f880
	s_cselect_b32 s43, 0x20080, s43
	s_cmp_eq_u32 s43, 0x22080
	s_cselect_b32 s43, 0x19880, s43
	s_add_i32 s39, s39, 0x2000
	s_cmp_eq_u32 s39, 0x1f880
	s_cselect_b32 s39, 0x20080, s39
	s_cmp_eq_u32 s39, 0x22080
	s_cselect_b32 s39, 0x19880, s39
	s_add_i32 s45, s45, 32
	s_add_i32 s41, s41, -1
	s_add_i32 s10, s45, 0x9f
	s_cmp_gt_i32 s10, s51
	s_cselect_b32 s11, 2, 0
	s_add_i32 s10, s45, 0x1f1
	s_cmp_le_i32 s10, s51
	s_cselect_b32 s10, 2, 0
	s_and_b32 s10, s10, s4
	s_or_b32 s11, s11, s10
	s_lshr_b32 s10, s45, 6
	v_bfe_u32 v0, v244, s10, 1
	v_cmp_ne_u32_e32 vcc, 0, v0
	s_cmp_lg_u64 vcc, 0
	s_cselect_b32 s10, 1, 0
	s_lshr_b32 s9, s11, 1
	s_or_b32 s10, s10, s9
	s_cmp_le_i32 s45, s15
	s_cselect_b32 s10, s10, 0
	s_cmp_ge_i32 s45, s40
	s_cselect_b32 s10, s10, 0
	s_or_b32 s12, s11, s10
	s_cmp_lg_u32 s41, 0
	s_cbranch_scc1 .Lat_xtop
.Lat_xexit:
	s_bitcmp1_b32 s44, 0
	s_cbranch_scc0 .Lat_done
	s_bitcmp1_b32 s44, 1
	s_cbranch_scc0 .Lat_nogi_xx
	s_mul_i32 s8, s38, 5
	s_lshl_b32 s9, s45, 2
	s_add_i32 s8, s8, s9
	s_add_i32 s8, s8, 0x228b0
	v_add_u32_e32 v116, s8, v246
	v_add_u32_e32 v117, 0xa50, v116
	ds_read2_b32 v[222:223], v116 offset0:0 offset1:1
	ds_read2_b32 v[224:225], v116 offset0:2 offset1:3
	ds_read2_b32 v[226:227], v116 offset0:16 offset1:17
	ds_read2_b32 v[228:229], v116 offset0:18 offset1:19
	ds_read2_b32 v[230:231], v117 offset0:0 offset1:1
	ds_read2_b32 v[232:233], v117 offset0:2 offset1:3
	ds_read2_b32 v[234:235], v117 offset0:16 offset1:17
	ds_read2_b32 v[236:237], v117 offset0:18 offset1:19
.Lat_nogi_xx:
	s_bitcmp1_b32 s44, 1
	s_cbranch_scc0 .Lat_noga_xx
	s_waitcnt lgkmcnt(0)
	v_add_f32_e32 v100, v100, v222
	v_add_f32_e32 v101, v101, v223
	v_add_f32_e32 v102, v102, v224
	v_add_f32_e32 v103, v103, v225
	v_add_f32_e32 v104, v104, v226
	v_add_f32_e32 v105, v105, v227
	v_add_f32_e32 v106, v106, v228
	v_add_f32_e32 v107, v107, v229
	v_add_f32_e32 v108, v108, v230
	v_add_f32_e32 v109, v109, v231
	v_add_f32_e32 v110, v110, v232
	v_add_f32_e32 v111, v111, v233
	v_add_f32_e32 v112, v112, v234
	v_add_f32_e32 v113, v113, v235
	v_add_f32_e32 v114, v114, v236
	v_add_f32_e32 v115, v115, v237

; template <bool SEL, bool GEN>
; DI void attn_step(const KF& kv, const int kb, const int t, const int lane, const bool selbit,
;                   const LAS float* tabh, const half8 (&q)[2][2], f32x4 (&O)[2][4], const float (&nR)[2], float (&l)[2]) {
;     ...
;   for (int hp = 0; hp < 2; ++hp) {
;     float nm = nR[hp];
;     if (SEL) nm = selbit ? nm : MASKV;
;     const f32x4 c0 = {nm, nm, nm, nm};
; #pragma unroll
;     for (int kt = 0; kt < 2; ++kt) {
;       s[hp][kt] = MFMA16(kv.k[kt][0], q[hp][0], c0);
;       s[hp][kt] = MFMA16(kv.k[kt][1], q[hp][1], s[hp][kt]);
;     }
;   }
;   if (GEN) {
;     const int d0 = t - kb - fq * 4;
; #pragma unroll
;     for (int kt = 0; kt < 2; ++kt)
; #pragma unroll
;       for (int j = 0; j < 4; ++j) {
;         const int dist = d0 - (kt * 16 + j);
; DI void attn_phase(const Params& p, const int layer, const int wid_s) {
;     ...
;         asm volatile("s_waitcnt vmcnt(0)" ::: "memory");
;         __syncthreads();
;         RING_ISSUE(0); RING_ISSUE(1);
; #pragma unroll 1
;         for (int si = 0; si < nsteps; ++si) {
;           asm volatile("s_waitcnt vmcnt(1) lgkmcnt(0)" ::: "memory");
;           __builtin_amdgcn_s_barrier();
;           asm volatile("" ::: "memory");
;           RING_ISSUE(si + 2);
;           const int kb = kb0 + si * 32;
;           if (kb > kmax_w || kb < lo_w) continue;
;           if (br == 1 && kb + 31 + 128 <= t0 && __ballot((selmask >> (kb >> 6)) & 1u) == 0ull) continue;
;           LAS unsigned char* slotp = ring + (si % 3) * 8192;
;           KF kv;
; #pragma unroll
;           for (int kt = 0; kt < 2; ++kt)
; #pragma unroll
;             for (int ks = 0; ks < 2; ++ks) kv.k[kt][ks] = *(const LAS half8*)(slotp + kread[kt][ks]);
; #pragma unroll
;           for (int dt = 0; dt < 4; ++dt) kv.v[dt] = *(const LAS half8*)(slotp + vread[dt]);
;           if (br == 1) {
;             const bool bit = (selmask >> (kb >> 6)) & 1u;
;             if (kb + 31 + 128 <= t0) attn_step<true, false>(kv, kb, t, lane, bit, tabh, q, O, nRs, l);
;             else attn_step<true, true>(kv, kb, t, lane, bit, tabh, q, O, nRs, l);
;           } else {
;             const bool gen = (kb + 31 + 128 > t0) || (kb + 512 <= t0 + 15);
;             if (!gen) attn_step<false, false>(kv, kb, t, lane, true, tabh, q, O, nRw, l);
;             else attn_step<false, true>(kv, kb, t, lane, true, tabh, q, O, nRw, l);
;           }
.Lat_ytop:
	s_waitcnt vmcnt(1)
	s_barrier
	s_bitcmp1_b32 s12, 0
	s_cbranch_scc0 .Lat_yskip
	s_bitcmp1_b32 s12, 1
	s_cbranch_scc0 .Lat_nogi_yt
	s_mul_i32 s8, s38, 5
	s_lshl_b32 s9, s45, 2
	s_add_i32 s8, s8, s9
	s_add_i32 s8, s8, 0x22930
	v_add_u32_e32 v116, s8, v246
	v_add_u32_e32 v117, 0xa50, v116
	ds_read2_b32 v[222:223], v116 offset0:0 offset1:1
	ds_read2_b32 v[224:225], v116 offset0:2 offset1:3
	ds_read2_b32 v[226:227], v116 offset0:16 offset1:17
	ds_read2_b32 v[228:229], v116 offset0:18 offset1:19
	ds_read2_b32 v[230:231], v117 offset0:0 offset1:1
	ds_read2_b32 v[232:233], v117 offset0:2 offset1:3
	ds_read2_b32 v[234:235], v117 offset0:16 offset1:17
	ds_read2_b32 v[236:237], v117 offset0:18 offset1:19
.Lat_nogi_yt:
	v_add_u32_e32 v0, s39, v185
	v_add_u32_e32 v64, s39, v184
	v_add_u32_e32 v65, s39, v183
	ds_read_b128 v[96:99], v0
	ds_read_b128 v[92:95], v64
	ds_read_b128 v[88:91], v0 offset:2048
	ds_read_b128 v[84:87], v64 offset:2048
	s_lshr_b32 s10, s45, 6
	s_cmp_eq_u32 s10, s13
	s_cbranch_scc1 .Lat_cok_y
	s_mov_b32 s13, s10
	v_bfe_u32 v66, v244, s10, 1
	v_cmp_ne_u32_e32 vcc, 0, v66
	s_nop 1
	v_cndmask_b32_e32 v128, v4, v242, vcc
	v_cndmask_b32_e32 v132, v4, v243, vcc
	v_cndmask_b32_e32 v129, v4, v242, vcc
	v_cndmask_b32_e32 v133, v4, v243, vcc
	v_cndmask_b32_e32 v130, v4, v242, vcc
	v_cndmask_b32_e32 v134, v4, v243, vcc
	v_cndmask_b32_e32 v131, v4, v242, vcc
	v_cndmask_b32_e32 v135, v4, v243, vcc
.Lat_cok_y:
	s_bitcmp1_b32 s44, 0
	s_cbranch_scc0 .Lat_yb
	s_waitcnt lgkmcnt(4)
	v_mfma_f32_16x16x32_f16 v[60:63], v[80:83], v[120:123], v[60:63]
	v_add_f32_e32 v214, v214, v198
	v_add_f32_e32 v215, v215, v199
	v_add_f32_e32 v216, v216, v200
	v_mfma_f32_16x16x32_f16 v[56:59], v[76:79], v[120:123], v[56:59]
	v_add_f32_e32 v217, v217, v201
	v_add_f32_e32 v214, v214, v202
	v_add_f32_e32 v215, v215, v203
	v_mfma_f32_16x16x32_f16 v[52:55], v[72:75], v[120:123], v[52:55]
	v_add_f32_e32 v216, v216, v204
	v_add_f32_e32 v217, v217, v205
	v_add_f32_e32 v218, v218, v206
	v_mfma_f32_16x16x32_f16 v[48:51], v[68:71], v[120:123], v[48:51]
	v_add_f32_e32 v219, v219, v207
	v_add_f32_e32 v220, v220, v208
	v_add_f32_e32 v221, v221, v209
	v_mfma_f32_16x16x32_f16 v[44:47], v[80:83], v[124:127], v[44:47]
	v_add_f32_e32 v218, v218, v210
	v_add_f32_e32 v219, v219, v211
	v_add_f32_e32 v220, v220, v212
	v_mfma_f32_16x16x32_f16 v[40:43], v[76:79], v[124:127], v[40:43]
	v_add_f32_e32 v221, v221, v213
	s_add_i32 s8, s45, 64
	s_min_i32 s8, s8, s14
	v_mfma_f32_16x16x32_f16 v[36:39], v[72:75], v[124:127], v[36:39]
	s_mul_i32 s8, s8, s42
	s_mov_b32 s9, 0
	v_lshl_add_u64 v[238:239], v[240:241], 0, s[8:9]
	v_mfma_f32_16x16x32_f16 v[32:35], v[68:71], v[124:127], v[32:35]
	s_add_i32 m0, s43, s22
	s_nop 0
	global_load_lds_dwordx4 v[238:239], off
	s_waitcnt lgkmcnt(0)
	s_and_b32 s44, s12, 2
	s_or_b32 s44, s44, 1
	v_mfma_f32_16x16x32_f16 v[100:103], v[96:99], v[8:11], v[128:131]
	s_add_i32 s43, s43, 0x2000
	s_cmp_eq_u32 s43, 0x1f880
	s_cselect_b32 s43, 0x20080, s43
	s_cmp_eq_u32 s43, 0x22080
	v_mfma_f32_16x16x32_f16 v[104:107], v[88:91], v[8:11], v[128:131]
	s_cselect_b32 s43, 0x19880, s43
	s_add_i32 s39, s39, 0x2000
	s_cmp_eq_u32 s39, 0x1f880
	s_cselect_b32 s39, 0x20080, s39
	v_mfma_f32_16x16x32_f16 v[108:111], v[96:99], v[16:19], v[132:135]
	s_cmp_eq_u32 s39, 0x22080
	s_cselect_b32 s39, 0x19880, s39
	s_add_i32 s45, s45, 32
	s_add_i32 s41, s41, -1
	v_mfma_f32_16x16x32_f16 v[112:115], v[88:91], v[16:19], v[132:135]
	s_add_i32 s10, s45, 0x9f
	s_cmp_gt_i32 s10, s51
	s_cselect_b32 s11, 2, 0
	s_add_i32 s10, s45, 0x1f1
	v_mfma_f32_16x16x32_f16 v[100:103], v[92:95], v[12:15], v[100:103]
	s_cmp_le_i32 s10, s51
	s_cselect_b32 s10, 2, 0
	s_and_b32 s10, s10, s4
	s_or_b32 s11, s11, s10
	v_mfma_f32_16x16x32_f16 v[104:107], v[84:87], v[12:15], v[104:107]
	s_lshr_b32 s10, s45, 6
	v_bfe_u32 v0, v244, s10, 1
	v_cmp_ne_u32_e32 vcc, 0, v0
	s_cmp_lg_u64 vcc, 0
	v_mfma_f32_16x16x32_f16 v[108:111], v[92:95], v[20:23], v[108:111]
	s_cselect_b32 s10, 1, 0
	s_lshr_b32 s9, s11, 1
	s_or_b32 s10, s10, s9
	s_cmp_le_i32 s45, s15
	v_mfma_f32_16x16x32_f16 v[112:115], v[84:87], v[20:23], v[112:115]
	s_cselect_b32 s10, s10, 0
	s_cmp_ge_i32 s45, s40
	s_cselect_b32 s10, s10, 0
	s_or_b32 s12, s11, s10
	ds_read_b128 v[80:83], v65 offset:4096
	ds_read_b128 v[76:79], v65 offset:5120
	ds_read_b128 v[72:75], v65 offset:6144
	ds_read_b128 v[68:71], v65 offset:7168
	s_bitcmp1_b32 s44, 1
	s_cbranch_scc0 .Lat_noga_ya
	v_add_f32_e32 v100, v100, v222
	v_add_f32_e32 v101, v101, v223
	v_add_f32_e32 v102, v102, v224
	v_add_f32_e32 v103, v103, v225
	v_add_f32_e32 v104, v104, v226
	v_add_f32_e32 v105, v105, v227
	v_add_f32_e32 v106, v106, v228
	v_add_f32_e32 v107, v107, v229
	v_add_f32_e32 v108, v108, v230
	v_add_f32_e32 v109, v109, v231
	v_add_f32_e32 v110, v110, v232
	v_add_f32_e32 v111, v111, v233
	v_add_f32_e32 v112, v112, v234
	v_add_f32_e32 v113, v113, v235
	v_add_f32_e32 v114, v114, v236
	v_add_f32_e32 v115, v115, v237

; template <bool SEL, bool GEN>
; DI void attn_step(const KF& kv, const int kb, const int t, const int lane, const bool selbit,
;                   const LAS float* tabh, const half8 (&q)[2][2], f32x4 (&O)[2][4], const float (&nR)[2], float (&l)[2]) {
;     ...
;   for (int hp = 0; hp < 2; ++hp) {
;     float nm = nR[hp];
;     if (SEL) nm = selbit ? nm : MASKV;
;     const f32x4 c0 = {nm, nm, nm, nm};
; #pragma unroll
;     for (int kt = 0; kt < 2; ++kt) {
;       s[hp][kt] = MFMA16(kv.k[kt][0], q[hp][0], c0);
;       s[hp][kt] = MFMA16(kv.k[kt][1], q[hp][1], s[hp][kt]);
;     }
;   }
;   if (GEN) {
;     const int d0 = t - kb - fq * 4;
; #pragma unroll
;     for (int kt = 0; kt < 2; ++kt)
; #pragma unroll
;       for (int j = 0; j < 4; ++j) {
;         const int dist = d0 - (kt * 16 + j);
; DI void attn_phase(const Params& p, const int layer, const int wid_s) {
;     ...
;         asm volatile("s_waitcnt vmcnt(0)" ::: "memory");
;         __syncthreads();
;         RING_ISSUE(0); RING_ISSUE(1);
; #pragma unroll 1
;         for (int si = 0; si < nsteps; ++si) {
;           asm volatile("s_waitcnt vmcnt(1) lgkmcnt(0)" ::: "memory");
;           __builtin_amdgcn_s_barrier();
;           asm volatile("" ::: "memory");
;           RING_ISSUE(si + 2);
;           const int kb = kb0 + si * 32;
;           if (kb > kmax_w || kb < lo_w) continue;
;           if (br == 1 && kb + 31 + 128 <= t0 && __ballot((selmask >> (kb >> 6)) & 1u) == 0ull) continue;
;           LAS unsigned char* slotp = ring + (si % 3) * 8192;
;           KF kv;
; #pragma unroll
;           for (int kt = 0; kt < 2; ++kt)
; #pragma unroll
;             for (int ks = 0; ks < 2; ++ks) kv.k[kt][ks] = *(const LAS half8*)(slotp + kread[kt][ks]);
; #pragma unroll
;           for (int dt = 0; dt < 4; ++dt) kv.v[dt] = *(const LAS half8*)(slotp + vread[dt]);
;           if (br == 1) {
;             const bool bit = (selmask >> (kb >> 6)) & 1u;
;             if (kb + 31 + 128 <= t0) attn_step<true, false>(kv, kb, t, lane, bit, tabh, q, O, nRs, l);
;             else attn_step<true, true>(kv, kb, t, lane, bit, tabh, q, O, nRs, l);
;           } else {
;             const bool gen = (kb + 31 + 128 > t0) || (kb + 512 <= t0 + 15);
;             if (!gen) attn_step<false, false>(kv, kb, t, lane, true, tabh, q, O, nRw, l);
;             else attn_step<false, true>(kv, kb, t, lane, true, tabh, q, O, nRw, l);
;           }
.Lat_yb:
	s_waitcnt lgkmcnt(0)
	s_and_b32 s44, s12, 2
	s_or_b32 s44, s44, 1
	v_mfma_f32_16x16x32_f16 v[100:103], v[96:99], v[8:11], v[128:131]
	s_add_i32 s8, s45, 64
	s_min_i32 s8, s8, s14
	s_mul_i32 s8, s8, s42
	s_mov_b32 s9, 0
	v_lshl_add_u64 v[238:239], v[240:241], 0, s[8:9]
	v_mfma_f32_16x16x32_f16 v[104:107], v[88:91], v[8:11], v[128:131]
	s_add_i32 m0, s43, s22
	s_nop 0
	global_load_lds_dwordx4 v[238:239], off
	s_add_i32 s43, s43, 0x2000
	s_cmp_eq_u32 s43, 0x1f880
	v_mfma_f32_16x16x32_f16 v[108:111], v[96:99], v[16:19], v[132:135]
	s_cselect_b32 s43, 0x20080, s43
	s_cmp_eq_u32 s43, 0x22080
	s_cselect_b32 s43, 0x19880, s43
	s_add_i32 s39, s39, 0x2000
	s_cmp_eq_u32 s39, 0x1f880
	v_mfma_f32_16x16x32_f16 v[112:115], v[88:91], v[16:19], v[132:135]
	s_cselect_b32 s39, 0x20080, s39
	s_cmp_eq_u32 s39, 0x22080
	s_cselect_b32 s39, 0x19880, s39
	s_add_i32 s45, s45, 32
	s_add_i32 s41, s41, -1
	v_mfma_f32_16x16x32_f16 v[100:103], v[92:95], v[12:15], v[100:103]
	s_add_i32 s10, s45, 0x9f
	s_cmp_gt_i32 s10, s51
	s_cselect_b32 s11, 2, 0
	s_add_i32 s10, s45, 0x1f1
	s_cmp_le_i32 s10, s51
	v_mfma_f32_16x16x32_f16 v[104:107], v[84:87], v[12:15], v[104:107]
	s_cselect_b32 s10, 2, 0
	s_and_b32 s10, s10, s4
	s_or_b32 s11, s11, s10
	s_lshr_b32 s10, s45, 6
	v_bfe_u32 v0, v244, s10, 1
	v_mfma_f32_16x16x32_f16 v[108:111], v[92:95], v[20:23], v[108:111]
	v_cmp_ne_u32_e32 vcc, 0, v0
	s_cmp_lg_u64 vcc, 0
	s_cselect_b32 s10, 1, 0
	s_lshr_b32 s9, s11, 1
	s_or_b32 s10, s10, s9
	v_mfma_f32_16x16x32_f16 v[112:115], v[84:87], v[20:23], v[112:115]
	s_cmp_le_i32 s45, s15
	s_cselect_b32 s10, s10, 0
	s_cmp_ge_i32 s45, s40
	s_cselect_b32 s10, s10, 0
	s_or_b32 s12, s11, s10
	ds_read_b128 v[80:83], v65 offset:4096
	ds_read_b128 v[76:79], v65 offset:5120
	ds_read_b128 v[72:75], v65 offset:6144
	ds_read_b128 v[68:71], v65 offset:7168
	s_bitcmp1_b32 s44, 1
	s_cbranch_scc0 .Lat_noga_yb
	v_add_f32_e32 v100, v100, v222
	v_add_f32_e32 v101, v101, v223
	v_add_f32_e32 v102, v102, v224
	v_add_f32_e32 v103, v103, v225
	v_add_f32_e32 v104, v104, v226
	v_add_f32_e32 v105, v105, v227
	v_add_f32_e32 v106, v106, v228
	v_add_f32_e32 v107, v107, v229
	v_add_f32_e32 v108, v108, v230
	v_add_f32_e32 v109, v109, v231
	v_add_f32_e32 v110, v110, v232
	v_add_f32_e32 v111, v111, v233
	v_add_f32_e32 v112, v112, v234
	v_add_f32_e32 v113, v113, v235
	v_add_f32_e32 v114, v114, v236
	v_add_f32_e32 v115, v115, v237

; #define LAS __attribute__((address_space(3)))
; template <bool SEL, bool GEN>
; DI void attn_step(const KF& kv, const int kb, const int t, const int lane, const bool selbit,
;                   const LAS float* tabh, const half8 (&q)[2][2], f32x4 (&O)[2][4], const float (&nR)[2], float (&l)[2]) {
;     ...
;   for (int hp = 0; hp < 2; ++hp) {
;     f32x4 p0, p1;
; #pragma unroll
;     for (int j = 0; j < 4; ++j) { p0[j] = __builtin_amdgcn_exp2f(s[hp][0][j]); p1[j] = __builtin_amdgcn_exp2f(s[hp][1][j]); }
;     l[hp] += ((p0[0] + p0[1]) + (p0[2] + p0[3])) + ((p1[0] + p1[1]) + (p1[2] + p1[3]));
;     pf[hp] = pack8(p0, p1);
;   }
; #pragma unroll
;   for (int dt = 0; dt < 4; ++dt)
; #pragma unroll
;     for (int hp = 0; hp < 2; ++hp) O[hp][dt] = MFMA16(kv.v[dt], pf[hp], O[hp][dt]);
; DI void attn_phase(const Params& p, const int layer, const int wid_s) {
;     ...
;         asm volatile("s_waitcnt vmcnt(0)" ::: "memory");
;         __syncthreads();
;         RING_ISSUE(0); RING_ISSUE(1);
; #pragma unroll 1
;         for (int si = 0; si < nsteps; ++si) {
;           asm volatile("s_waitcnt vmcnt(1) lgkmcnt(0)" ::: "memory");
;           __builtin_amdgcn_s_barrier();
;           asm volatile("" ::: "memory");
;           RING_ISSUE(si + 2);
;           const int kb = kb0 + si * 32;
;           if (kb > kmax_w || kb < lo_w) continue;
;           if (br == 1 && kb + 31 + 128 <= t0 && __ballot((selmask >> (kb >> 6)) & 1u) == 0ull) continue;
;           LAS unsigned char* slotp = ring + (si % 3) * 8192;
;           KF kv;
; #pragma unroll
;           for (int kt = 0; kt < 2; ++kt)
; #pragma unroll
;             for (int ks = 0; ks < 2; ++ks) kv.k[kt][ks] = *(const LAS half8*)(slotp + kread[kt][ks]);
; #pragma unroll
;           for (int dt = 0; dt < 4; ++dt) kv.v[dt] = *(const LAS half8*)(slotp + vread[dt]);
;           if (br == 1) {
;             const bool bit = (selmask >> (kb >> 6)) & 1u;
;             if (kb + 31 + 128 <= t0) attn_step<true, false>(kv, kb, t, lane, bit, tabh, q, O, nRs, l);
;             else attn_step<true, true>(kv, kb, t, lane, bit, tabh, q, O, nRs, l);
;           } else {
;             const bool gen = (kb + 31 + 128 > t0) || (kb + 512 <= t0 + 15);
;             if (!gen) attn_step<false, false>(kv, kb, t, lane, true, tabh, q, O, nRw, l);
;             else attn_step<false, true>(kv, kb, t, lane, true, tabh, q, O, nRw, l);
;           }
.Lat_yskip:
	s_bitcmp1_b32 s44, 0
	s_cbranch_scc0 .Lat_yd
	s_waitcnt lgkmcnt(0)
	v_mfma_f32_16x16x32_f16 v[60:63], v[80:83], v[120:123], v[60:63]
	v_add_f32_e32 v214, v214, v198
	v_add_f32_e32 v215, v215, v199
	v_add_f32_e32 v216, v216, v200
	v_add_f32_e32 v217, v217, v201
	v_add_f32_e32 v214, v214, v202
	v_add_f32_e32 v215, v215, v203
	v_add_f32_e32 v216, v216, v204
	v_mfma_f32_16x16x32_f16 v[56:59], v[76:79], v[120:123], v[56:59]
	v_add_f32_e32 v217, v217, v205
	v_add_f32_e32 v218, v218, v206
	v_add_f32_e32 v219, v219, v207
	v_add_f32_e32 v220, v220, v208
	v_add_f32_e32 v221, v221, v209
	v_add_f32_e32 v218, v218, v210
	v_add_f32_e32 v219, v219, v211
	v_mfma_f32_16x16x32_f16 v[52:55], v[72:75], v[120:123], v[52:55]
	v_add_f32_e32 v220, v220, v212
	v_add_f32_e32 v221, v221, v213
	s_add_i32 s8, s45, 64
	s_min_i32 s8, s8, s14
	s_mul_i32 s8, s8, s42
	s_mov_b32 s9, 0
	v_lshl_add_u64 v[238:239], v[240:241], 0, s[8:9]
	v_mfma_f32_16x16x32_f16 v[48:51], v[68:71], v[120:123], v[48:51]
	s_add_i32 m0, s43, s22
	s_nop 0
	global_load_lds_dwordx4 v[238:239], off
	s_add_i32 s43, s43, 0x2000
	s_cmp_eq_u32 s43, 0x1f880
	s_cselect_b32 s43, 0x20080, s43
	s_cmp_eq_u32 s43, 0x22080
	v_mfma_f32_16x16x32_f16 v[44:47], v[80:83], v[124:127], v[44:47]
	s_cselect_b32 s43, 0x19880, s43
	s_add_i32 s39, s39, 0x2000
	s_cmp_eq_u32 s39, 0x1f880
	s_cselect_b32 s39, 0x20080, s39
	s_cmp_eq_u32 s39, 0x22080
	s_cselect_b32 s39, 0x19880, s39
	s_add_i32 s45, s45, 32
	v_mfma_f32_16x16x32_f16 v[40:43], v[76:79], v[124:127], v[40:43]
	s_add_i32 s41, s41, -1
	s_add_i32 s10, s45, 0x9f
	s_cmp_gt_i32 s10, s51
	s_cselect_b32 s11, 2, 0
	s_add_i32 s10, s45, 0x1f1
	s_cmp_le_i32 s10, s51
	s_cselect_b32 s10, 2, 0
	v_mfma_f32_16x16x32_f16 v[36:39], v[72:75], v[124:127], v[36:39]
	s_and_b32 s10, s10, s4
	s_or_b32 s11, s11, s10
	s_lshr_b32 s10, s45, 6
	v_bfe_u32 v0, v244, s10, 1
	v_cmp_ne_u32_e32 vcc, 0, v0
	s_cmp_lg_u64 vcc, 0
	s_cselect_b32 s10, 1, 0
	v_mfma_f32_16x16x32_f16 v[32:35], v[68:71], v[124:127], v[32:35]
	s_lshr_b32 s9, s11, 1
	s_or_b32 s10, s10, s9
	s_cmp_le_i32 s45, s15
	s_cselect_b32 s10, s10, 0
	s_cmp_ge_i32 s45, s40
	s_cselect_b32 s10, s10, 0
	s_or_b32 s12, s11, s10
	s_mov_b32 s44, 0
	s_cmp_lg_u32 s41, 0
	s_cbranch_scc1 .Lat_ytop
	s_branch .Lat_yexit

	.amdhsa_kernel _Z9hymba_fwd6Params
		.amdhsa_group_segment_fixed_size 32752
		.amdhsa_private_segment_fixed_size 0
		.amdhsa_kernarg_size 424
		.amdhsa_user_sgpr_count 2
		.amdhsa_user_sgpr_dispatch_ptr 0
		.amdhsa_user_sgpr_queue_ptr 0
		.amdhsa_user_sgpr_kernarg_segment_ptr 1
		.amdhsa_user_sgpr_dispatch_id 0
		.amdhsa_user_sgpr_kernarg_preload_length 0
		.amdhsa_user_sgpr_kernarg_preload_offset 0
		.amdhsa_user_sgpr_private_segment_size 0
		.amdhsa_uses_dynamic_stack 0
		.amdhsa_enable_private_segment 0
		.amdhsa_system_sgpr_workgroup_id_x 1
		.amdhsa_system_sgpr_workgroup_id_y 0
		.amdhsa_system_sgpr_workgroup_id_z 0
		.amdhsa_system_sgpr_workgroup_info 0
		.amdhsa_system_vgpr_workitem_id 2
		.amdhsa_next_free_vgpr 256
		.amdhsa_next_free_sgpr 100
		.amdhsa_accum_offset 256
		.amdhsa_reserve_vcc 1
		.amdhsa_float_round_mode_32 0
		.amdhsa_float_round_mode_16_64 0
		.amdhsa_float_denorm_mode_32 3
		.amdhsa_float_denorm_mode_16_64 3
		.amdhsa_dx10_clamp 1
		.amdhsa_ieee_mode 1
		.amdhsa_fp16_overflow 0
		.amdhsa_tg_split 0
		.amdhsa_exception_fp_ieee_invalid_op 0
		.amdhsa_exception_fp_denorm_src 0
		.amdhsa_exception_fp_ieee_div_zero 0
		.amdhsa_exception_fp_ieee_overflow 0
		.amdhsa_exception_fp_ieee_underflow 0
		.amdhsa_exception_fp_ieee_inexact 0
		.amdhsa_exception_int_div_zero 0
	.end_amdhsa_kernel

amdhsa.kernels:
  - .agpr_count:     0
    .args:
      - .offset:         0
        .size:           168
        .value_kind:     by_value
      - .offset:         168
        .size:           4
        .value_kind:     hidden_block_count_x
      - .offset:         172
        .size:           4
        .value_kind:     hidden_block_count_y
      - .offset:         176
        .size:           4
        .value_kind:     hidden_block_count_z
      - .offset:         180
        .size:           2
        .value_kind:     hidden_group_size_x
      - .offset:         182
        .size:           2
        .value_kind:     hidden_group_size_y
      - .offset:         184
        .size:           2
        .value_kind:     hidden_group_size_z
      - .offset:         186
        .size:           2
        .value_kind:     hidden_remainder_x
      - .offset:         188
        .size:           2
        .value_kind:     hidden_remainder_y
      - .offset:         190
        .size:           2
        .value_kind:     hidden_remainder_z
      - .offset:         208
        .size:           8
        .value_kind:     hidden_global_offset_x
      - .offset:         216
        .size:           8
        .value_kind:     hidden_global_offset_y
      - .offset:         224
        .size:           8
        .value_kind:     hidden_global_offset_z
      - .offset:         232
        .size:           2
        .value_kind:     hidden_grid_dims
      - .offset:         256
        .size:           8
        .value_kind:     hidden_multigrid_sync_arg
      - .offset:         288
        .size:           4
        .value_kind:     hidden_dynamic_lds_size
    .group_segment_fixed_size: 32752
    .kernarg_segment_align: 8
    .kernarg_segment_size: 424
    .language:       OpenCL C
    .language_version:
      - 2
      - 0
    .max_flat_workgroup_size: 512
    .name:           _Z9hymba_fwd6Params
    .private_segment_fixed_size: 0
    .sgpr_count:     106
    .sgpr_spill_count: 267
    .symbol:         _Z9hymba_fwd6Params.kd
    .uniform_work_group_size: 1
    .uses_dynamic_stack: false
    .vgpr_count:     256
    .vgpr_spill_count: 0
    .wavefront_size: 64
